# speedup vs baseline: 1.0035x; 1.0035x over previous
; __device__ __forceinline__ void attn2_block(const BlockRef& R, char* lds) {
;     ...
;   for (int t = 0; t < NT; ++t) {
;     const int bo = (t & 1) * AT_BUF;
;     const int k0 = t * 64;
;     if (k0 <= qlo + 31) {
;       const bool needmask = k0 + 63 > qlo;
; #pragma unroll
;       for (int ks = 0; ks < 2; ++ks) {
;         f32x4 s[2][2];
; #pragma unroll
;         for (int kt = 0; kt < 2; ++kt) { s[kt][0] = f32x4{0.f, 0.f, 0.f, 0.f}; s[kt][1] = f32x4{0.f, 0.f, 0.f, 0.f}; }
;         {
;           const char* kr0 = kbase0 + bo + (ks * 2) * 16 * AT_KSTR;
;           const char* kr1 = kbase1 + bo + (ks * 2) * 16 * AT_KSTR;
;           bf16x8 ka0 = *(const bf16x8*)(kr0), ka1 = *(const bf16x8*)(kr0 + 16 * AT_KSTR);
; #pragma unroll
;           for (int k = 0; k < 6; ++k) {
;             bf16x8 kn0, kn1;
;             if (k < 5) {
;               const char* nb = (((k + 1) & 1) ? kr1 : kr0) + ((k + 1) >> 1) * 128;
;               kn0 = *(const bf16x8*)(nb); kn1 = *(const bf16x8*)(nb + 16 * AT_KSTR);
;             }
;             __builtin_amdgcn_sched_barrier(0);
;             s[0][0] = __builtin_amdgcn_mfma_f32_16x16x32_bf16(ka0, qf[0][k], s[0][0], 0, 0, 0);
;             s[0][1] = __builtin_amdgcn_mfma_f32_16x16x32_bf16(ka0, qf[1][k], s[0][1], 0, 0, 0);
;             s[1][0] = __builtin_amdgcn_mfma_f32_16x16x32_bf16(ka1, qf[0][k], s[1][0], 0, 0, 0);
;             s[1][1] = __builtin_amdgcn_mfma_f32_16x16x32_bf16(ka1, qf[1][k], s[1][1], 0, 0, 0);
;             __builtin_amdgcn_sched_barrier(0);
;             if (k < 5) { ka0 = kn0; ka1 = kn1; }
;           }
.LBB0_497:
	s_add_i32 s95, s95, 1
	s_bitcmp1_b32 s95, 0
	s_cselect_b32 s70, 0xa000, 0
	s_xor_b32 s71, s70, 0xa000
	s_sub_i32 s2, s77, 64
	s_cmp_gt_u32 s2, s62
	s_cbranch_scc1 .Latt4_skip
	v_add_u32_e32 v179, s71, v168
	v_add_u32_e32 v3, s71, v169
	ds_read_b128 v[180:183], v179
	ds_read_b128 v[184:187], v179 offset:6144
	ds_read_b128 v[188:191], v3
	ds_read_b128 v[192:195], v3 offset:6144
	ds_read_b128 v[196:199], v179 offset:128
	ds_read_b128 v[200:203], v179 offset:6272
	ds_read_b128 v[204:207], v3 offset:128
	ds_read_b128 v[208:211], v3 offset:6272
	ds_read_b128 v[212:215], v179 offset:256
	ds_read_b128 v[216:219], v179 offset:6400
	ds_read_b128 v[220:223], v3 offset:256
	ds_read_b128 v[224:227], v3 offset:6400
	s_bitcmp1_b32 s95, 0
	s_cbranch_scc0 .Latt4_g0_even
	s_waitcnt lgkmcnt(11)
	v_mfma_f32_16x16x32_bf16 v[148:151], v[180:183], v[40:43], 0
	v_add_u32_e32 v2, s70, v240
	v_add_u32_e32 v255, s70, v241
	v_mfma_f32_16x16x32_bf16 v[140:143], v[180:183], v[48:51], 0
	v_add_u32_e32 v0, s70, v242
	s_waitcnt vmcnt(9)
	s_waitcnt lgkmcnt(10)
	v_mfma_f32_16x16x32_bf16 v[144:147], v[184:187], v[40:43], 0
	ds_write_b128 v2, v[64:67]
	v_mfma_f32_16x16x32_bf16 v[136:139], v[184:187], v[48:51], 0
	s_waitcnt vmcnt(7)
	s_waitcnt lgkmcnt(10)
	v_mfma_f32_16x16x32_bf16 v[148:151], v[188:191], v[32:35], v[148:151]
	ds_write_b128 v2, v[68:71] offset:12288
	v_mfma_f32_16x16x32_bf16 v[140:143], v[188:191], v[44:47], v[140:143]
	ds_write_b128 v255, v[60:63]
	s_waitcnt lgkmcnt(11)
	v_mfma_f32_16x16x32_bf16 v[144:147], v[192:195], v[32:35], v[144:147]
	s_waitcnt vmcnt(5)
	v_perm_b32 v2, v52, v56, s83
	v_mfma_f32_16x16x32_bf16 v[136:139], v[192:195], v[44:47], v[136:139]
	ds_write_b32 v0, v2 offset:24576
	v_perm_b32 v2, v52, v56, s84
	v_xor_b32_e32 v255, 16, v0
	s_waitcnt lgkmcnt(11)
	v_mfma_f32_16x16x32_bf16 v[148:151], v[196:199], v[24:27], v[148:151]
	ds_write_b32 v255, v2 offset:24704
	v_mfma_f32_16x16x32_bf16 v[140:143], v[196:199], v[36:39], v[140:143]
	v_perm_b32 v2, v53, v57, s83
	v_xor_b32_e32 v255, 32, v0
	s_waitcnt lgkmcnt(11)
	v_mfma_f32_16x16x32_bf16 v[144:147], v[200:203], v[24:27], v[144:147]
	ds_write_b32 v255, v2 offset:24832
	v_perm_b32 v2, v53, v57, s84
	v_xor_b32_e32 v255, 48, v0
	v_mfma_f32_16x16x32_bf16 v[136:139], v[200:203], v[36:39], v[136:139]
	ds_write_b32 v255, v2 offset:24960
	v_perm_b32 v2, v54, v58, s83
	v_xor_b32_e32 v255, 64, v0
	s_waitcnt lgkmcnt(12)
	v_mfma_f32_16x16x32_bf16 v[148:151], v[204:207], v[16:19], v[148:151]
	ds_write_b32 v255, v2 offset:25088
	v_mfma_f32_16x16x32_bf16 v[140:143], v[204:207], v[28:31], v[140:143]
	v_perm_b32 v2, v54, v58, s84
	v_xor_b32_e32 v255, s85, v0
	s_waitcnt lgkmcnt(12)
	v_mfma_f32_16x16x32_bf16 v[144:147], v[208:211], v[16:19], v[144:147]
	ds_write_b32 v255, v2 offset:25216
	v_perm_b32 v2, v55, v59, s83
	v_xor_b32_e32 v255, s86, v0
	v_mfma_f32_16x16x32_bf16 v[136:139], v[208:211], v[28:31], v[136:139]
	ds_write_b32 v255, v2 offset:25344
	v_perm_b32 v2, v55, v59, s84
	v_xor_b32_e32 v255, s80, v0
	s_waitcnt lgkmcnt(13)
	v_mfma_f32_16x16x32_bf16 v[148:151], v[212:215], v[8:11], v[148:151]
	ds_write_b32 v255, v2 offset:25472
	v_mfma_f32_16x16x32_bf16 v[140:143], v[212:215], v[20:23], v[140:143]
	s_add_u32 s2, s58, s66
	s_addc_u32 s3, s59, s67
	s_waitcnt lgkmcnt(13)
	v_mfma_f32_16x16x32_bf16 v[144:147], v[216:219], v[8:11], v[144:147]
	s_add_u32 s2, s2, 0x17680000
	s_addc_u32 s3, s3, 0
	s_add_u32 s96, s58, s68
	s_addc_u32 s97, s59, s69
	v_mfma_f32_16x16x32_bf16 v[136:139], v[216:219], v[20:23], v[136:139]
	s_add_u32 s96, s96, 0x20000
	s_addc_u32 s97, s97, 0
	s_add_u32 s98, s2, 0x40000
	s_addc_u32 s99, s3, 0
	s_waitcnt lgkmcnt(12)
	v_mfma_f32_16x16x32_bf16 v[148:151], v[220:223], v[4:7], v[148:151]
	s_add_u32 s100, s2, 0x2000
	s_addc_u32 s101, s3, 0
	v_mfma_f32_16x16x32_bf16 v[140:143], v[220:223], v[12:15], v[140:143]
	global_load_dwordx4 v[64:67], v243, s[2:3]
	global_load_dwordx4 v[60:63], v249, s[96:97]
	s_waitcnt lgkmcnt(11)
	v_mfma_f32_16x16x32_bf16 v[144:147], v[224:227], v[4:7], v[144:147]
	global_load_dwordx4 v[68:71], v243, s[98:99]
	global_load_dwordx4 v[52:55], v254, s[2:3] offset:256
	global_load_dwordx4 v[56:59], v254, s[100:101] offset:256
	v_mfma_f32_16x16x32_bf16 v[136:139], v[224:227], v[12:15], v[136:139]
	s_branch .Latt4_g1
; __device__ __forceinline__ void attn2_block(const BlockRef& R, char* lds) {
;     ...
;       for (int ks = 0; ks < 2; ++ks) {
;         f32x4 s[2][2];
; #pragma unroll
;         for (int kt = 0; kt < 2; ++kt) { s[kt][0] = f32x4{0.f, 0.f, 0.f, 0.f}; s[kt][1] = f32x4{0.f, 0.f, 0.f, 0.f}; }
;         {
;           const char* kr0 = kbase0 + bo + (ks * 2) * 16 * AT_KSTR;
;           const char* kr1 = kbase1 + bo + (ks * 2) * 16 * AT_KSTR;
;           bf16x8 ka0 = *(const bf16x8*)(kr0), ka1 = *(const bf16x8*)(kr0 + 16 * AT_KSTR);
; #pragma unroll
;           for (int k = 0; k < 6; ++k) {
;             bf16x8 kn0, kn1;
;             if (k < 5) {
;               const char* nb = (((k + 1) & 1) ? kr1 : kr0) + ((k + 1) >> 1) * 128;
;               kn0 = *(const bf16x8*)(nb); kn1 = *(const bf16x8*)(nb + 16 * AT_KSTR);
;             }
;             __builtin_amdgcn_sched_barrier(0);
;             s[0][0] = __builtin_amdgcn_mfma_f32_16x16x32_bf16(ka0, qf[0][k], s[0][0], 0, 0, 0);
;             s[0][1] = __builtin_amdgcn_mfma_f32_16x16x32_bf16(ka0, qf[1][k], s[0][1], 0, 0, 0);
;             s[1][0] = __builtin_amdgcn_mfma_f32_16x16x32_bf16(ka1, qf[0][k], s[1][0], 0, 0, 0);
;             s[1][1] = __builtin_amdgcn_mfma_f32_16x16x32_bf16(ka1, qf[1][k], s[1][1], 0, 0, 0);
;             __builtin_amdgcn_sched_barrier(0);
;             if (k < 5) { ka0 = kn0; ka1 = kn1; }
;           }
;         }
;         __builtin_amdgcn_sched_barrier(0);
;         bf16x8 pb[2];
; #pragma unroll
;         for (int qt = 0; qt < 2; ++qt) {
;           const int qpos = qlo + qt * 16 + fr;
;           if (needmask) {
;             asm volatile("" ::: "memory");
; #pragma unroll
;             for (int kt = 0; kt < 2; ++kt)
; #pragma unroll
;               for (int j = 0; j < 4; ++j)
;                 if (k0 + (ks * 2 + kt) * 16 + fq * 4 + j > qpos) s[kt][qt][j] = -__builtin_inff();
;           }
.Latt4_g0_even:
	s_waitcnt lgkmcnt(11)
	v_mfma_f32_16x16x32_bf16 v[148:151], v[180:183], v[40:43], 0
	v_add_u32_e32 v2, s70, v240
	v_add_u32_e32 v255, s70, v241
	v_mfma_f32_16x16x32_bf16 v[140:143], v[180:183], v[48:51], 0
	v_add_u32_e32 v0, s70, v242
	s_waitcnt vmcnt(9)
	s_waitcnt lgkmcnt(10)
	v_mfma_f32_16x16x32_bf16 v[144:147], v[184:187], v[40:43], 0
	ds_write_b128 v2, v[228:231]
	v_mfma_f32_16x16x32_bf16 v[136:139], v[184:187], v[48:51], 0
	s_waitcnt vmcnt(7)
	s_waitcnt lgkmcnt(10)
	v_mfma_f32_16x16x32_bf16 v[148:151], v[188:191], v[32:35], v[148:151]
	ds_write_b128 v2, v[232:235] offset:12288
	v_mfma_f32_16x16x32_bf16 v[140:143], v[188:191], v[44:47], v[140:143]
	ds_write_b128 v255, v[236:239]
	s_waitcnt lgkmcnt(11)
	v_mfma_f32_16x16x32_bf16 v[144:147], v[192:195], v[32:35], v[144:147]
	s_waitcnt vmcnt(5)
	v_perm_b32 v2, v244, v250, s83
	v_mfma_f32_16x16x32_bf16 v[136:139], v[192:195], v[44:47], v[136:139]
	ds_write_b32 v0, v2 offset:24576
	v_perm_b32 v2, v244, v250, s84
	v_xor_b32_e32 v255, 16, v0
	s_waitcnt lgkmcnt(11)
	v_mfma_f32_16x16x32_bf16 v[148:151], v[196:199], v[24:27], v[148:151]
	ds_write_b32 v255, v2 offset:24704
	v_mfma_f32_16x16x32_bf16 v[140:143], v[196:199], v[36:39], v[140:143]
	v_perm_b32 v2, v245, v251, s83
	v_xor_b32_e32 v255, 32, v0
	s_waitcnt lgkmcnt(11)
	v_mfma_f32_16x16x32_bf16 v[144:147], v[200:203], v[24:27], v[144:147]
	ds_write_b32 v255, v2 offset:24832
	v_perm_b32 v2, v245, v251, s84
	v_xor_b32_e32 v255, 48, v0
	v_mfma_f32_16x16x32_bf16 v[136:139], v[200:203], v[36:39], v[136:139]
	ds_write_b32 v255, v2 offset:24960
	v_perm_b32 v2, v246, v252, s83
	v_xor_b32_e32 v255, 64, v0
	s_waitcnt lgkmcnt(12)
	v_mfma_f32_16x16x32_bf16 v[148:151], v[204:207], v[16:19], v[148:151]
	ds_write_b32 v255, v2 offset:25088
	v_mfma_f32_16x16x32_bf16 v[140:143], v[204:207], v[28:31], v[140:143]
	v_perm_b32 v2, v246, v252, s84
	v_xor_b32_e32 v255, s85, v0
	s_waitcnt lgkmcnt(12)
	v_mfma_f32_16x16x32_bf16 v[144:147], v[208:211], v[16:19], v[144:147]
	ds_write_b32 v255, v2 offset:25216
	v_perm_b32 v2, v247, v253, s83
	v_xor_b32_e32 v255, s86, v0
	v_mfma_f32_16x16x32_bf16 v[136:139], v[208:211], v[28:31], v[136:139]
	ds_write_b32 v255, v2 offset:25344
	v_perm_b32 v2, v247, v253, s84
	v_xor_b32_e32 v255, s80, v0
	s_waitcnt lgkmcnt(13)
	v_mfma_f32_16x16x32_bf16 v[148:151], v[212:215], v[8:11], v[148:151]
	ds_write_b32 v255, v2 offset:25472
	v_mfma_f32_16x16x32_bf16 v[140:143], v[212:215], v[20:23], v[140:143]
	s_waitcnt lgkmcnt(13)
	v_mfma_f32_16x16x32_bf16 v[144:147], v[216:219], v[8:11], v[144:147]
	v_mfma_f32_16x16x32_bf16 v[136:139], v[216:219], v[20:23], v[136:139]
	s_waitcnt lgkmcnt(12)
	v_mfma_f32_16x16x32_bf16 v[148:151], v[220:223], v[4:7], v[148:151]
	v_mfma_f32_16x16x32_bf16 v[140:143], v[220:223], v[12:15], v[140:143]
	s_waitcnt lgkmcnt(11)
	v_mfma_f32_16x16x32_bf16 v[144:147], v[224:227], v[4:7], v[144:147]
	v_mfma_f32_16x16x32_bf16 v[136:139], v[224:227], v[12:15], v[136:139]
	s_cmp_eq_u32 s94, s95
	s_cbranch_scc1 .Latt4_noload
	s_add_u32 s2, s58, s66
	s_addc_u32 s3, s59, s67
	s_add_u32 s2, s2, 0x17680000
	s_addc_u32 s3, s3, 0
	s_add_u32 s96, s58, s68
	s_addc_u32 s97, s59, s69
	s_add_u32 s96, s96, 0x20000
	s_addc_u32 s97, s97, 0
	s_add_u32 s98, s2, 0x40000
	s_addc_u32 s99, s3, 0
	s_add_u32 s100, s2, 0x2000
	s_addc_u32 s101, s3, 0
	global_load_dwordx4 v[228:231], v243, s[2:3]
	global_load_dwordx4 v[236:239], v249, s[96:97]
	global_load_dwordx4 v[232:235], v243, s[98:99]
	global_load_dwordx4 v[244:247], v254, s[2:3] offset:256
	global_load_dwordx4 v[250:253], v254, s[100:101] offset:256
.Latt4_noload:
.Latt4_g1:
	s_add_i32 s3, s77, -1
	s_cmp_gt_u32 s3, s79
	s_cselect_b64 s[100:101], -1, 0
	ds_read_b128 v[180:183], v179 offset:12288
	ds_read_b128 v[184:187], v179 offset:18432
	ds_read_b128 v[188:191], v3 offset:12288
	ds_read_b128 v[192:195], v3 offset:18432
	v_add_u32_e32 v255, s71, v167
	v_add_u32_e32 v255, v255, v170
	s_waitcnt lgkmcnt(12)
	ds_read_b128 v[212:215], v255 offset:24576
	ds_read_b128 v[216:219], v255 offset:26624
	ds_read_b128 v[220:223], v255 offset:28672
	s_waitcnt lgkmcnt(12)
	ds_read_b128 v[224:227], v255 offset:30720
	s_andn2_b64 vcc, exec, s[100:101]
	s_cbranch_vccnz .Latt3_nomask_1
	v_add_u32_e32 v2, s77, v156
	v_subrev_u32_e32 v2, 64, v2
	v_add_u32_e32 v0, 0, v2
	v_cmp_le_u32_e32 vcc, v0, v175
	s_nop 1
	v_cndmask_b32_e32 v148, v173, v148, vcc
	v_add_u32_e32 v0, 1, v2
	v_cmp_le_u32_e32 vcc, v0, v175
	s_nop 1
	v_cndmask_b32_e32 v149, v173, v149, vcc
	v_add_u32_e32 v0, 2, v2
	v_cmp_le_u32_e32 vcc, v0, v175
	s_nop 1
	v_cndmask_b32_e32 v150, v173, v150, vcc
	v_add_u32_e32 v0, 3, v2
	v_cmp_le_u32_e32 vcc, v0, v175
	s_nop 1
	v_cndmask_b32_e32 v151, v173, v151, vcc
	v_add_u32_e32 v0, 16, v2
	v_cmp_le_u32_e32 vcc, v0, v175
	s_nop 1
	v_cndmask_b32_e32 v144, v173, v144, vcc
	v_add_u32_e32 v0, 17, v2
	v_cmp_le_u32_e32 vcc, v0, v175
	s_nop 1
	v_cndmask_b32_e32 v145, v173, v145, vcc
	v_add_u32_e32 v0, 18, v2
	v_cmp_le_u32_e32 vcc, v0, v175
	s_nop 1
	v_cndmask_b32_e32 v146, v173, v146, vcc
	v_add_u32_e32 v0, 19, v2
	v_cmp_le_u32_e32 vcc, v0, v175
	s_nop 1
	v_cndmask_b32_e32 v147, v173, v147, vcc
; __device__ __forceinline__ void attn2_block(const BlockRef& R, char* lds) {
;     ...
;         for (int qt = 0; qt < 2; ++qt) {
;           const int qpos = qlo + qt * 16 + fr;
;           if (needmask) {
;             asm volatile("" ::: "memory");
; #pragma unroll
;             for (int kt = 0; kt < 2; ++kt)
; #pragma unroll
;               for (int j = 0; j < 4; ++j)
;                 if (k0 + (ks * 2 + kt) * 16 + fq * 4 + j > qpos) s[kt][qt][j] = -__builtin_inff();
;           }
;           float mx = fmaxf(fmaxf(fmaxf(s[0][qt][0], s[0][qt][1]), fmaxf(s[0][qt][2], s[0][qt][3])),
;                            fmaxf(fmaxf(s[1][qt][0], s[1][qt][1]), fmaxf(s[1][qt][2], s[1][qt][3])));
;           if (!__all(mx - m[qt] <= 8.f)) {
;             { auto rr = __builtin_amdgcn_permlane16_swap(__float_as_uint(mx), __float_as_uint(mx), false, false);
;               mx = fmaxf(__uint_as_float(rr[0]), __uint_as_float(rr[1])); }
;             { auto rr = __builtin_amdgcn_permlane32_swap(__float_as_uint(mx), __float_as_uint(mx), false, false);
;               mx = fmaxf(__uint_as_float(rr[0]), __uint_as_float(rr[1])); }
;             const float mn = fmaxf(m[qt], mx);
;             const float alpha = __builtin_amdgcn_exp2f(m[qt] - mn);
;             m[qt] = mn;
;             l[qt] *= alpha;
; #pragma unroll
;             for (int dt = 0; dt < 8; ++dt) { o[qt][dt][0] *= alpha; o[qt][dt][1] *= alpha; o[qt][dt][2] *= alpha; o[qt][dt][3] *= alpha; }
;           }
;           float ps = 0.f;
; #pragma unroll
;           for (int kt = 0; kt < 2; ++kt)
; #pragma unroll
;             for (int j = 0; j < 4; ++j) { const float p = __builtin_amdgcn_exp2f(s[kt][qt][j] - m[qt]); s[kt][qt][j] = p; ps += p; }
;           l[qt] += ps;
;           u32x4 w = {cvtpk_bf16(s[0][qt][0], s[0][qt][1]), cvtpk_bf16(s[0][qt][2], s[0][qt][3]),
;                      cvtpk_bf16(s[1][qt][0], s[1][qt][1]), cvtpk_bf16(s[1][qt][2], s[1][qt][3])};
;           pb[qt] = *reinterpret_cast<bf16x8*>(&w);
.Latt3_nomask_1:
	v_max3_f32 v0, v148, v149, v150
	v_max3_f32 v2, v151, v144, v145
	s_waitcnt lgkmcnt(7)
	v_mfma_f32_16x16x32_bf16 v[196:199], v[180:183], v[40:43], 0
	v_max3_f32 v2, v146, v147, v2
	v_max_f32_e32 v0, v0, v2
	v_sub_f32_e32 v2, v0, v177
	v_mfma_f32_16x16x32_bf16 v[200:203], v[180:183], v[48:51], 0
	v_cmp_ge_f32_e32 vcc, s88, v2
	s_cmp_eq_u64 vcc, exec
	s_cbranch_scc1 .Latt3_norescale_2
	v_mov_b32_e32 v2, v0
	s_nop 1
	v_permlane16_swap_b32_e32 v0, v2
	v_max_f32_e32 v0, v0, v2
	v_mov_b32_e32 v2, v0
	s_nop 1
	v_permlane32_swap_b32_e32 v0, v2
	v_max3_f32 v2, v177, v0, v2
	v_sub_f32_e32 v0, v177, v2
	v_exp_f32_e32 v0, v0
	v_mov_b32_e32 v177, v2
	s_nop 0
	v_mul_f32_e32 v178, v178, v0
	v_pk_mul_f32 v[134:135], v[134:135], v[0:1] op_sel_hi:[1,0]
	v_pk_mul_f32 v[132:133], v[132:133], v[0:1] op_sel_hi:[1,0]
	v_pk_mul_f32 v[130:131], v[130:131], v[0:1] op_sel_hi:[1,0]
	v_pk_mul_f32 v[128:129], v[128:129], v[0:1] op_sel_hi:[1,0]
	v_pk_mul_f32 v[126:127], v[126:127], v[0:1] op_sel_hi:[1,0]
	v_pk_mul_f32 v[124:125], v[124:125], v[0:1] op_sel_hi:[1,0]
	v_pk_mul_f32 v[122:123], v[122:123], v[0:1] op_sel_hi:[1,0]
	v_pk_mul_f32 v[120:121], v[120:121], v[0:1] op_sel_hi:[1,0]
	v_pk_mul_f32 v[118:119], v[118:119], v[0:1] op_sel_hi:[1,0]
	v_pk_mul_f32 v[116:117], v[116:117], v[0:1] op_sel_hi:[1,0]
	v_pk_mul_f32 v[114:115], v[114:115], v[0:1] op_sel_hi:[1,0]
	v_pk_mul_f32 v[112:113], v[112:113], v[0:1] op_sel_hi:[1,0]
	v_pk_mul_f32 v[110:111], v[110:111], v[0:1] op_sel_hi:[1,0]
	v_pk_mul_f32 v[108:109], v[108:109], v[0:1] op_sel_hi:[1,0]
	v_pk_mul_f32 v[106:107], v[106:107], v[0:1] op_sel_hi:[1,0]
	v_pk_mul_f32 v[104:105], v[104:105], v[0:1] op_sel_hi:[1,0]
.Latt3_norescale_2:
	v_sub_f32_e32 v148, v148, v177
	s_waitcnt lgkmcnt(6)
	v_mfma_f32_16x16x32_bf16 v[204:207], v[184:187], v[40:43], 0
	v_sub_f32_e32 v149, v149, v177
	v_exp_f32_e32 v148, v148
	v_sub_f32_e32 v150, v150, v177
	v_mfma_f32_16x16x32_bf16 v[208:211], v[184:187], v[48:51], 0
	ds_read_b128 v[180:183], v179 offset:12416
	ds_read_b128 v[184:187], v179 offset:18560
	v_exp_f32_e32 v149, v149
	v_sub_f32_e32 v151, v151, v177
	v_exp_f32_e32 v150, v150
	s_waitcnt lgkmcnt(7)
	v_mfma_f32_16x16x32_bf16 v[196:199], v[188:191], v[32:35], v[196:199]
	v_sub_f32_e32 v144, v144, v177
	v_exp_f32_e32 v151, v151
	v_sub_f32_e32 v145, v145, v177
	v_mfma_f32_16x16x32_bf16 v[200:203], v[188:191], v[44:47], v[200:203]
	v_exp_f32_e32 v144, v144
	v_sub_f32_e32 v146, v146, v177
	v_exp_f32_e32 v145, v145
	s_waitcnt lgkmcnt(6)
	v_mfma_f32_16x16x32_bf16 v[204:207], v[192:195], v[32:35], v[204:207]
	v_sub_f32_e32 v147, v147, v177
	v_exp_f32_e32 v146, v146
	v_exp_f32_e32 v147, v147
	v_mfma_f32_16x16x32_bf16 v[208:211], v[192:195], v[44:47], v[208:211]
	ds_read_b128 v[188:191], v3 offset:12416
	ds_read_b128 v[192:195], v3 offset:18560
	v_add_f32_e32 v0, v148, v149
	v_add_f32_e32 v0, v150, v0
	v_add_f32_e32 v0, v151, v0
	s_waitcnt lgkmcnt(3)
	v_mfma_f32_16x16x32_bf16 v[196:199], v[180:183], v[24:27], v[196:199]
	v_add_f32_e32 v0, v144, v0
	v_add_f32_e32 v0, v145, v0
	v_add_f32_e32 v0, v146, v0
	v_mfma_f32_16x16x32_bf16 v[200:203], v[180:183], v[36:39], v[200:203]
	v_add_f32_e32 v0, v147, v0
	v_add_f32_e32 v178, v178, v0
	v_cvt_pk_bf16_f32 v148, v148, v149
	s_waitcnt lgkmcnt(2)
	v_mfma_f32_16x16x32_bf16 v[204:207], v[184:187], v[24:27], v[204:207]
	v_cvt_pk_bf16_f32 v149, v150, v151
	v_cvt_pk_bf16_f32 v150, v144, v145
	v_cvt_pk_bf16_f32 v151, v146, v147
	v_mfma_f32_16x16x32_bf16 v[208:211], v[184:187], v[36:39], v[208:211]
	ds_read_b128 v[180:183], v179 offset:12544
	ds_read_b128 v[184:187], v179 offset:18688
	s_andn2_b64 vcc, exec, s[100:101]
	s_cbranch_vccnz .Latt3_nomask_3
	v_add_u32_e32 v2, s77, v156
	v_subrev_u32_e32 v2, 64, v2
	v_add_u32_e32 v0, 0, v2
	v_cmp_le_u32_e32 vcc, v0, v159
	s_nop 1
	v_cndmask_b32_e32 v140, v173, v140, vcc
	v_add_u32_e32 v0, 1, v2
	v_cmp_le_u32_e32 vcc, v0, v159
	s_nop 1
	v_cndmask_b32_e32 v141, v173, v141, vcc
	v_add_u32_e32 v0, 2, v2
	v_cmp_le_u32_e32 vcc, v0, v159
	s_nop 1
	v_cndmask_b32_e32 v142, v173, v142, vcc
	v_add_u32_e32 v0, 3, v2
	v_cmp_le_u32_e32 vcc, v0, v159
	s_nop 1
	v_cndmask_b32_e32 v143, v173, v143, vcc
	v_add_u32_e32 v0, 16, v2
	v_cmp_le_u32_e32 vcc, v0, v159
	s_nop 1
	v_cndmask_b32_e32 v136, v173, v136, vcc
	v_add_u32_e32 v0, 17, v2
	v_cmp_le_u32_e32 vcc, v0, v159
	s_nop 1
	v_cndmask_b32_e32 v137, v173, v137, vcc
	v_add_u32_e32 v0, 18, v2
	v_cmp_le_u32_e32 vcc, v0, v159
	s_nop 1
	v_cndmask_b32_e32 v138, v173, v138, vcc
	v_add_u32_e32 v0, 19, v2
	v_cmp_le_u32_e32 vcc, v0, v159
	s_nop 1
	v_cndmask_b32_e32 v139, v173, v139, vcc
.Latt3_nomask_3:
	v_max3_f32 v0, v140, v141, v142
	v_max3_f32 v2, v143, v136, v137
	s_waitcnt lgkmcnt(3)
	v_mfma_f32_16x16x32_bf16 v[196:199], v[188:191], v[16:19], v[196:199]
	v_max3_f32 v2, v138, v139, v2
	v_max_f32_e32 v0, v0, v2
	v_sub_f32_e32 v2, v0, v176
	v_mfma_f32_16x16x32_bf16 v[200:203], v[188:191], v[28:31], v[200:203]
	v_cmp_ge_f32_e32 vcc, s88, v2
	s_cmp_eq_u64 vcc, exec
	s_cbranch_scc1 .Latt3_norescale_4
	v_mov_b32_e32 v2, v0
	s_nop 1
	v_permlane16_swap_b32_e32 v0, v2
	v_max_f32_e32 v0, v0, v2
	v_mov_b32_e32 v2, v0
	s_nop 1
	v_permlane32_swap_b32_e32 v0, v2
	v_max3_f32 v2, v176, v0, v2
	v_sub_f32_e32 v0, v176, v2
	v_exp_f32_e32 v0, v0
	v_mov_b32_e32 v176, v2
	s_nop 0
	v_mul_f32_e32 v174, v174, v0
	v_pk_mul_f32 v[102:103], v[102:103], v[0:1] op_sel_hi:[1,0]
	v_pk_mul_f32 v[100:101], v[100:101], v[0:1] op_sel_hi:[1,0]
	v_pk_mul_f32 v[98:99], v[98:99], v[0:1] op_sel_hi:[1,0]
	v_pk_mul_f32 v[96:97], v[96:97], v[0:1] op_sel_hi:[1,0]
	v_pk_mul_f32 v[94:95], v[94:95], v[0:1] op_sel_hi:[1,0]
	v_pk_mul_f32 v[92:93], v[92:93], v[0:1] op_sel_hi:[1,0]
	v_pk_mul_f32 v[90:91], v[90:91], v[0:1] op_sel_hi:[1,0]
	v_pk_mul_f32 v[88:89], v[88:89], v[0:1] op_sel_hi:[1,0]
	v_pk_mul_f32 v[86:87], v[86:87], v[0:1] op_sel_hi:[1,0]
	v_pk_mul_f32 v[84:85], v[84:85], v[0:1] op_sel_hi:[1,0]
	v_pk_mul_f32 v[82:83], v[82:83], v[0:1] op_sel_hi:[1,0]
	v_pk_mul_f32 v[80:81], v[80:81], v[0:1] op_sel_hi:[1,0]
	v_pk_mul_f32 v[78:79], v[78:79], v[0:1] op_sel_hi:[1,0]
	v_pk_mul_f32 v[76:77], v[76:77], v[0:1] op_sel_hi:[1,0]
	v_pk_mul_f32 v[74:75], v[74:75], v[0:1] op_sel_hi:[1,0]
	v_pk_mul_f32 v[72:73], v[72:73], v[0:1] op_sel_hi:[1,0]
; __device__ __forceinline__ void attn2_block(const BlockRef& R, char* lds) {
;     ...
;         for (int qt = 0; qt < 2; ++qt) {
;           const int qpos = qlo + qt * 16 + fr;
;           if (needmask) {
;             asm volatile("" ::: "memory");
; #pragma unroll
;             for (int kt = 0; kt < 2; ++kt)
; #pragma unroll
;               for (int j = 0; j < 4; ++j)
;                 if (k0 + (ks * 2 + kt) * 16 + fq * 4 + j > qpos) s[kt][qt][j] = -__builtin_inff();
;           }
;           float mx = fmaxf(fmaxf(fmaxf(s[0][qt][0], s[0][qt][1]), fmaxf(s[0][qt][2], s[0][qt][3])),
;                            fmaxf(fmaxf(s[1][qt][0], s[1][qt][1]), fmaxf(s[1][qt][2], s[1][qt][3])));
;           if (!__all(mx - m[qt] <= 8.f)) {
;             { auto rr = __builtin_amdgcn_permlane16_swap(__float_as_uint(mx), __float_as_uint(mx), false, false);
;               mx = fmaxf(__uint_as_float(rr[0]), __uint_as_float(rr[1])); }
;             { auto rr = __builtin_amdgcn_permlane32_swap(__float_as_uint(mx), __float_as_uint(mx), false, false);
;               mx = fmaxf(__uint_as_float(rr[0]), __uint_as_float(rr[1])); }
;             const float mn = fmaxf(m[qt], mx);
;             const float alpha = __builtin_amdgcn_exp2f(m[qt] - mn);
;             m[qt] = mn;
;             l[qt] *= alpha;
; #pragma unroll
;             for (int dt = 0; dt < 8; ++dt) { o[qt][dt][0] *= alpha; o[qt][dt][1] *= alpha; o[qt][dt][2] *= alpha; o[qt][dt][3] *= alpha; }
;           }
;           float ps = 0.f;
; #pragma unroll
;           for (int kt = 0; kt < 2; ++kt)
; #pragma unroll
;             for (int j = 0; j < 4; ++j) { const float p = __builtin_amdgcn_exp2f(s[kt][qt][j] - m[qt]); s[kt][qt][j] = p; ps += p; }
;           l[qt] += ps;
;           u32x4 w = {cvtpk_bf16(s[0][qt][0], s[0][qt][1]), cvtpk_bf16(s[0][qt][2], s[0][qt][3]),
;                      cvtpk_bf16(s[1][qt][0], s[1][qt][1]), cvtpk_bf16(s[1][qt][2], s[1][qt][3])};
;           pb[qt] = *reinterpret_cast<bf16x8*>(&w);
;         }
; #pragma unroll
;         for (int dt = 0; dt < 8; ++dt) {
;           if ((dt & 3) == 0) __builtin_amdgcn_sched_barrier(0);
;           const bf16x8 a = *(const bf16x8*)((ks ? vbase1 : vbase0) + bo + dt * 16 * AT_VSTR);
;           o[0][dt] = __builtin_amdgcn_mfma_f32_16x16x32_bf16(a, pb[0], o[0][dt], 0, 0, 0);
.Latt3_norescale_4:
	v_sub_f32_e32 v140, v140, v176
	s_waitcnt lgkmcnt(2)
	v_mfma_f32_16x16x32_bf16 v[204:207], v[192:195], v[16:19], v[204:207]
	v_sub_f32_e32 v141, v141, v176
	v_exp_f32_e32 v140, v140
	v_sub_f32_e32 v142, v142, v176
	v_mfma_f32_16x16x32_bf16 v[208:211], v[192:195], v[28:31], v[208:211]
	ds_read_b128 v[188:191], v3 offset:12544
	ds_read_b128 v[192:195], v3 offset:18688
	v_exp_f32_e32 v141, v141
	v_sub_f32_e32 v143, v143, v176
	v_exp_f32_e32 v142, v142
	s_waitcnt lgkmcnt(3)
	v_mfma_f32_16x16x32_bf16 v[196:199], v[180:183], v[8:11], v[196:199]
	v_sub_f32_e32 v136, v136, v176
	v_exp_f32_e32 v143, v143
	v_sub_f32_e32 v137, v137, v176
	v_mfma_f32_16x16x32_bf16 v[200:203], v[180:183], v[20:23], v[200:203]
	v_exp_f32_e32 v136, v136
	v_sub_f32_e32 v138, v138, v176
	v_exp_f32_e32 v137, v137
	s_waitcnt lgkmcnt(2)
	v_mfma_f32_16x16x32_bf16 v[204:207], v[184:187], v[8:11], v[204:207]
	v_sub_f32_e32 v139, v139, v176
	v_exp_f32_e32 v138, v138
	v_exp_f32_e32 v139, v139
	v_mfma_f32_16x16x32_bf16 v[208:211], v[184:187], v[20:23], v[208:211]
	v_add_f32_e32 v0, v140, v141
	v_add_f32_e32 v0, v142, v0
	v_add_f32_e32 v0, v143, v0
	s_waitcnt lgkmcnt(1)
	v_mfma_f32_16x16x32_bf16 v[196:199], v[188:191], v[4:7], v[196:199]
	v_add_f32_e32 v0, v136, v0
	v_add_f32_e32 v0, v137, v0
	v_add_f32_e32 v0, v138, v0
	v_mfma_f32_16x16x32_bf16 v[200:203], v[188:191], v[12:15], v[200:203]
	v_add_f32_e32 v0, v139, v0
	v_add_f32_e32 v174, v174, v0
	v_cvt_pk_bf16_f32 v140, v140, v141
	s_waitcnt lgkmcnt(0)
	v_mfma_f32_16x16x32_bf16 v[204:207], v[192:195], v[4:7], v[204:207]
	v_cvt_pk_bf16_f32 v141, v142, v143
	v_cvt_pk_bf16_f32 v142, v136, v137
	v_cvt_pk_bf16_f32 v143, v138, v139
	v_mfma_f32_16x16x32_bf16 v[208:211], v[192:195], v[12:15], v[208:211]
	ds_read_b128 v[180:183], v255 offset:32768
	ds_read_b128 v[184:187], v255 offset:34816
	ds_read_b128 v[188:191], v255 offset:36864
	ds_read_b128 v[192:195], v255 offset:38912
	v_add_u32_e32 v255, s71, v167
	v_add_u32_e32 v255, v255, v171
	v_mov_b32_e32 v144, 1.0
	v_mov_b32_e32 v146, 1.0
	s_mov_b32 s98, 0
	s_andn2_b64 vcc, exec, s[100:101]
	s_cbranch_vccnz .Latt3_nomask_5
	v_add_u32_e32 v2, s77, v156
	v_subrev_u32_e32 v2, 32, v2
	v_add_u32_e32 v0, 0, v2
	v_cmp_le_u32_e32 vcc, v0, v175
	s_nop 1
	v_cndmask_b32_e32 v196, v173, v196, vcc
	v_add_u32_e32 v0, 1, v2
	v_cmp_le_u32_e32 vcc, v0, v175
	s_nop 1
	v_cndmask_b32_e32 v197, v173, v197, vcc
	v_add_u32_e32 v0, 2, v2
	v_cmp_le_u32_e32 vcc, v0, v175
	s_nop 1
	v_cndmask_b32_e32 v198, v173, v198, vcc
	v_add_u32_e32 v0, 3, v2
	v_cmp_le_u32_e32 vcc, v0, v175
	s_nop 1
	v_cndmask_b32_e32 v199, v173, v199, vcc
	v_add_u32_e32 v0, 16, v2
	v_cmp_le_u32_e32 vcc, v0, v175
	s_nop 1
	v_cndmask_b32_e32 v204, v173, v204, vcc
	v_add_u32_e32 v0, 17, v2
	v_cmp_le_u32_e32 vcc, v0, v175
	s_nop 1
	v_cndmask_b32_e32 v205, v173, v205, vcc
	v_add_u32_e32 v0, 18, v2
	v_cmp_le_u32_e32 vcc, v0, v175
	s_nop 1
	v_cndmask_b32_e32 v206, v173, v206, vcc
	v_add_u32_e32 v0, 19, v2
	v_cmp_le_u32_e32 vcc, v0, v175
	s_nop 1
	v_cndmask_b32_e32 v207, v173, v207, vcc
.Latt3_nomask_5:
	v_max3_f32 v0, v196, v197, v198
	v_max3_f32 v2, v199, v204, v205
	v_max3_f32 v2, v206, v207, v2
	v_max_f32_e32 v0, v0, v2
	v_mfma_f32_16x16x32_bf16 v[132:135], v[212:215], v[148:151], v[132:135]
	v_sub_f32_e32 v2, v0, v177
	v_cmp_ge_f32_e32 vcc, s88, v2
	s_cmp_eq_u64 vcc, exec
	s_cbranch_scc1 .Latt3_norescale_6
	v_mov_b32_e32 v2, v0
	s_nop 1
	v_permlane16_swap_b32_e32 v0, v2
	v_max_f32_e32 v0, v0, v2
	v_mov_b32_e32 v2, v0
	s_nop 1
	v_permlane32_swap_b32_e32 v0, v2
	v_max3_f32 v2, v177, v0, v2
	v_sub_f32_e32 v0, v177, v2
	v_exp_f32_e32 v144, v0
	v_mov_b32_e32 v177, v2
	s_mov_b32 s98, 1
	v_mul_f32_e32 v178, v178, v144
.Latt3_norescale_6:
	v_sub_f32_e32 v196, v196, v177
	v_sub_f32_e32 v197, v197, v177
	v_mfma_f32_16x16x32_bf16 v[100:103], v[212:215], v[140:143], v[100:103]
	v_exp_f32_e32 v196, v196
	v_sub_f32_e32 v198, v198, v177
	v_exp_f32_e32 v197, v197
	v_sub_f32_e32 v199, v199, v177
	v_exp_f32_e32 v198, v198
	v_mfma_f32_16x16x32_bf16 v[128:131], v[216:219], v[148:151], v[128:131]
	v_sub_f32_e32 v204, v204, v177
	v_exp_f32_e32 v199, v199
	v_sub_f32_e32 v205, v205, v177
	v_exp_f32_e32 v204, v204
	v_sub_f32_e32 v206, v206, v177
	v_mfma_f32_16x16x32_bf16 v[96:99], v[216:219], v[140:143], v[96:99]
	v_exp_f32_e32 v205, v205
	v_sub_f32_e32 v207, v207, v177
	v_exp_f32_e32 v206, v206
	v_exp_f32_e32 v207, v207
	v_add_f32_e32 v0, v196, v197
	v_mfma_f32_16x16x32_bf16 v[124:127], v[220:223], v[148:151], v[124:127]
	v_add_f32_e32 v0, v198, v0
	v_add_f32_e32 v0, v199, v0
	v_add_f32_e32 v0, v204, v0
	v_add_f32_e32 v0, v205, v0
	v_add_f32_e32 v0, v206, v0
	v_mfma_f32_16x16x32_bf16 v[92:95], v[220:223], v[140:143], v[92:95]
	v_add_f32_e32 v0, v207, v0
	v_add_f32_e32 v178, v178, v0
	v_cvt_pk_bf16_f32 v196, v196, v197
	v_cvt_pk_bf16_f32 v197, v198, v199
	v_cvt_pk_bf16_f32 v198, v204, v205
	v_mfma_f32_16x16x32_bf16 v[120:123], v[224:227], v[148:151], v[120:123]
	v_cvt_pk_bf16_f32 v199, v206, v207
	s_andn2_b64 vcc, exec, s[100:101]
	s_cbranch_vccnz .Latt3_nomask_7
	v_add_u32_e32 v2, s77, v156
	v_subrev_u32_e32 v2, 32, v2
	v_add_u32_e32 v0, 0, v2
	v_cmp_le_u32_e32 vcc, v0, v159
	s_nop 1
	v_cndmask_b32_e32 v200, v173, v200, vcc
	v_add_u32_e32 v0, 1, v2
	v_cmp_le_u32_e32 vcc, v0, v159
	s_nop 1
	v_cndmask_b32_e32 v201, v173, v201, vcc
	v_add_u32_e32 v0, 2, v2
	v_cmp_le_u32_e32 vcc, v0, v159
	s_nop 1
	v_cndmask_b32_e32 v202, v173, v202, vcc
	v_add_u32_e32 v0, 3, v2
	v_cmp_le_u32_e32 vcc, v0, v159
	s_nop 1
	v_cndmask_b32_e32 v203, v173, v203, vcc
	v_add_u32_e32 v0, 16, v2
	v_cmp_le_u32_e32 vcc, v0, v159
	s_nop 1
	v_cndmask_b32_e32 v208, v173, v208, vcc
	v_add_u32_e32 v0, 17, v2
	v_cmp_le_u32_e32 vcc, v0, v159
	s_nop 1
	v_cndmask_b32_e32 v209, v173, v209, vcc
	v_add_u32_e32 v0, 18, v2
	v_cmp_le_u32_e32 vcc, v0, v159
	s_nop 1
	v_cndmask_b32_e32 v210, v173, v210, vcc
	v_add_u32_e32 v0, 19, v2
	v_cmp_le_u32_e32 vcc, v0, v159
	s_nop 1
	v_cndmask_b32_e32 v211, v173, v211, vcc
; __device__ __forceinline__ void attn2_block(const BlockRef& R, char* lds) {
;     ...
;         for (int qt = 0; qt < 2; ++qt) {
;           const int qpos = qlo + qt * 16 + fr;
;           if (needmask) {
;             asm volatile("" ::: "memory");
; #pragma unroll
;             for (int kt = 0; kt < 2; ++kt)
; #pragma unroll
;               for (int j = 0; j < 4; ++j)
;                 if (k0 + (ks * 2 + kt) * 16 + fq * 4 + j > qpos) s[kt][qt][j] = -__builtin_inff();
;           }
;           float mx = fmaxf(fmaxf(fmaxf(s[0][qt][0], s[0][qt][1]), fmaxf(s[0][qt][2], s[0][qt][3])),
;                            fmaxf(fmaxf(s[1][qt][0], s[1][qt][1]), fmaxf(s[1][qt][2], s[1][qt][3])));
;           if (!__all(mx - m[qt] <= 8.f)) {
;             { auto rr = __builtin_amdgcn_permlane16_swap(__float_as_uint(mx), __float_as_uint(mx), false, false);
;               mx = fmaxf(__uint_as_float(rr[0]), __uint_as_float(rr[1])); }
;             { auto rr = __builtin_amdgcn_permlane32_swap(__float_as_uint(mx), __float_as_uint(mx), false, false);
;               mx = fmaxf(__uint_as_float(rr[0]), __uint_as_float(rr[1])); }
;             const float mn = fmaxf(m[qt], mx);
;             const float alpha = __builtin_amdgcn_exp2f(m[qt] - mn);
;             m[qt] = mn;
;             l[qt] *= alpha;
; #pragma unroll
;             for (int dt = 0; dt < 8; ++dt) { o[qt][dt][0] *= alpha; o[qt][dt][1] *= alpha; o[qt][dt][2] *= alpha; o[qt][dt][3] *= alpha; }
;           }
;           float ps = 0.f;
; #pragma unroll
;           for (int kt = 0; kt < 2; ++kt)
; #pragma unroll
;             for (int j = 0; j < 4; ++j) { const float p = __builtin_amdgcn_exp2f(s[kt][qt][j] - m[qt]); s[kt][qt][j] = p; ps += p; }
;           l[qt] += ps;
;           u32x4 w = {cvtpk_bf16(s[0][qt][0], s[0][qt][1]), cvtpk_bf16(s[0][qt][2], s[0][qt][3]),
;                      cvtpk_bf16(s[1][qt][0], s[1][qt][1]), cvtpk_bf16(s[1][qt][2], s[1][qt][3])};
;           pb[qt] = *reinterpret_cast<bf16x8*>(&w);
;         }
; #pragma unroll
;         for (int dt = 0; dt < 8; ++dt) {
;           if ((dt & 3) == 0) __builtin_amdgcn_sched_barrier(0);
;           const bf16x8 a = *(const bf16x8*)((ks ? vbase1 : vbase0) + bo + dt * 16 * AT_VSTR);
;           o[0][dt] = __builtin_amdgcn_mfma_f32_16x16x32_bf16(a, pb[0], o[0][dt], 0, 0, 0);
.Latt3_nomask_7:
	v_max3_f32 v0, v200, v201, v202
	v_max3_f32 v2, v203, v208, v209
	v_max3_f32 v2, v210, v211, v2
	v_mfma_f32_16x16x32_bf16 v[88:91], v[224:227], v[140:143], v[88:91]
	ds_read_b128 v[212:215], v255 offset:24576
	ds_read_b128 v[216:219], v255 offset:26624
	ds_read_b128 v[220:223], v255 offset:28672
	ds_read_b128 v[224:227], v255 offset:30720
	v_max_f32_e32 v0, v0, v2
	v_sub_f32_e32 v2, v0, v176
	v_cmp_ge_f32_e32 vcc, s88, v2
	s_cmp_eq_u64 vcc, exec
	s_cbranch_scc1 .Latt3_norescale_8
	v_mov_b32_e32 v2, v0
	s_nop 1
	v_permlane16_swap_b32_e32 v0, v2
	v_max_f32_e32 v0, v0, v2
	v_mov_b32_e32 v2, v0
	s_nop 1
	v_permlane32_swap_b32_e32 v0, v2
	v_max3_f32 v2, v176, v0, v2
	v_sub_f32_e32 v0, v176, v2
	v_exp_f32_e32 v146, v0
	v_mov_b32_e32 v176, v2
	s_mov_b32 s98, 1
	v_mul_f32_e32 v174, v174, v146
.Latt3_norescale_8:
	v_sub_f32_e32 v200, v200, v176
	s_waitcnt lgkmcnt(7)
	v_mfma_f32_16x16x32_bf16 v[116:119], v[180:183], v[148:151], v[116:119]
	v_sub_f32_e32 v201, v201, v176
	v_exp_f32_e32 v200, v200
	v_sub_f32_e32 v202, v202, v176
	v_exp_f32_e32 v201, v201
	v_sub_f32_e32 v203, v203, v176
	v_mfma_f32_16x16x32_bf16 v[84:87], v[180:183], v[140:143], v[84:87]
	v_exp_f32_e32 v202, v202
	v_sub_f32_e32 v208, v208, v176
	v_exp_f32_e32 v203, v203
	v_sub_f32_e32 v209, v209, v176
	v_exp_f32_e32 v208, v208
	s_waitcnt lgkmcnt(6)
	v_mfma_f32_16x16x32_bf16 v[112:115], v[184:187], v[148:151], v[112:115]
	v_sub_f32_e32 v210, v210, v176
	v_exp_f32_e32 v209, v209
	v_sub_f32_e32 v211, v211, v176
	v_exp_f32_e32 v210, v210
	v_exp_f32_e32 v211, v211
	v_mfma_f32_16x16x32_bf16 v[80:83], v[184:187], v[140:143], v[80:83]
	v_add_f32_e32 v0, v200, v201
	v_add_f32_e32 v0, v202, v0
	v_add_f32_e32 v0, v203, v0
	v_add_f32_e32 v0, v208, v0
	v_add_f32_e32 v0, v209, v0
	s_waitcnt lgkmcnt(5)
	v_mfma_f32_16x16x32_bf16 v[108:111], v[188:191], v[148:151], v[108:111]
	v_add_f32_e32 v0, v210, v0
	v_add_f32_e32 v0, v211, v0
	v_add_f32_e32 v174, v174, v0
	v_cvt_pk_bf16_f32 v200, v200, v201
	v_cvt_pk_bf16_f32 v201, v202, v203
	v_mfma_f32_16x16x32_bf16 v[76:79], v[188:191], v[140:143], v[76:79]
	v_cvt_pk_bf16_f32 v202, v208, v209
	v_cvt_pk_bf16_f32 v203, v210, v211
	s_waitcnt lgkmcnt(4)
	v_mfma_f32_16x16x32_bf16 v[104:107], v[192:195], v[148:151], v[104:107]
	v_mfma_f32_16x16x32_bf16 v[72:75], v[192:195], v[140:143], v[72:75]
	ds_read_b128 v[180:183], v255 offset:32768
	ds_read_b128 v[184:187], v255 offset:34816
	ds_read_b128 v[188:191], v255 offset:36864
	ds_read_b128 v[192:195], v255 offset:38912
	s_cmp_lg_u32 s98, 0
	s_cbranch_scc0 .Latt3_nodefer_9
	s_nop 7
	v_pk_mul_f32 v[134:135], v[134:135], v[144:145] op_sel_hi:[1,0]
	v_pk_mul_f32 v[132:133], v[132:133], v[144:145] op_sel_hi:[1,0]
	v_pk_mul_f32 v[130:131], v[130:131], v[144:145] op_sel_hi:[1,0]
	v_pk_mul_f32 v[128:129], v[128:129], v[144:145] op_sel_hi:[1,0]
	v_pk_mul_f32 v[126:127], v[126:127], v[144:145] op_sel_hi:[1,0]
	v_pk_mul_f32 v[124:125], v[124:125], v[144:145] op_sel_hi:[1,0]
	v_pk_mul_f32 v[122:123], v[122:123], v[144:145] op_sel_hi:[1,0]
	v_pk_mul_f32 v[120:121], v[120:121], v[144:145] op_sel_hi:[1,0]
	v_pk_mul_f32 v[118:119], v[118:119], v[144:145] op_sel_hi:[1,0]
	v_pk_mul_f32 v[116:117], v[116:117], v[144:145] op_sel_hi:[1,0]
	v_pk_mul_f32 v[114:115], v[114:115], v[144:145] op_sel_hi:[1,0]
	v_pk_mul_f32 v[112:113], v[112:113], v[144:145] op_sel_hi:[1,0]
	v_pk_mul_f32 v[110:111], v[110:111], v[144:145] op_sel_hi:[1,0]
	v_pk_mul_f32 v[108:109], v[108:109], v[144:145] op_sel_hi:[1,0]
	v_pk_mul_f32 v[106:107], v[106:107], v[144:145] op_sel_hi:[1,0]
	v_pk_mul_f32 v[104:105], v[104:105], v[144:145] op_sel_hi:[1,0]
	v_pk_mul_f32 v[102:103], v[102:103], v[146:147] op_sel_hi:[1,0]
	v_pk_mul_f32 v[100:101], v[100:101], v[146:147] op_sel_hi:[1,0]
	v_pk_mul_f32 v[98:99], v[98:99], v[146:147] op_sel_hi:[1,0]
	v_pk_mul_f32 v[96:97], v[96:97], v[146:147] op_sel_hi:[1,0]
	v_pk_mul_f32 v[94:95], v[94:95], v[146:147] op_sel_hi:[1,0]
	v_pk_mul_f32 v[92:93], v[92:93], v[146:147] op_sel_hi:[1,0]
	v_pk_mul_f32 v[90:91], v[90:91], v[146:147] op_sel_hi:[1,0]
	v_pk_mul_f32 v[88:89], v[88:89], v[146:147] op_sel_hi:[1,0]
	v_pk_mul_f32 v[86:87], v[86:87], v[146:147] op_sel_hi:[1,0]
	v_pk_mul_f32 v[84:85], v[84:85], v[146:147] op_sel_hi:[1,0]
	v_pk_mul_f32 v[82:83], v[82:83], v[146:147] op_sel_hi:[1,0]
	v_pk_mul_f32 v[80:81], v[80:81], v[146:147] op_sel_hi:[1,0]
	v_pk_mul_f32 v[78:79], v[78:79], v[146:147] op_sel_hi:[1,0]
	v_pk_mul_f32 v[76:77], v[76:77], v[146:147] op_sel_hi:[1,0]
	v_pk_mul_f32 v[74:75], v[74:75], v[146:147] op_sel_hi:[1,0]
	v_pk_mul_f32 v[72:73], v[72:73], v[146:147] op_sel_hi:[1,0]
	s_nop 1
; __device__ __forceinline__ void attn2_block(const BlockRef& R, char* lds) {
;     ...
; #pragma unroll
;         for (int dt = 0; dt < 8; ++dt) {
;           if ((dt & 3) == 0) __builtin_amdgcn_sched_barrier(0);
;           const bf16x8 a = *(const bf16x8*)((ks ? vbase1 : vbase0) + bo + dt * 16 * AT_VSTR);
;           o[0][dt] = __builtin_amdgcn_mfma_f32_16x16x32_bf16(a, pb[0], o[0][dt], 0, 0, 0);
;           o[1][dt] = __builtin_amdgcn_mfma_f32_16x16x32_bf16(a, pb[1], o[1][dt], 0, 0, 0);
;         }
;       }
;     }
;     if (t + 1 < NT) {
;       const int bn = ((t + 1) & 1) * AT_BUF;
;       AT_WRITE(bn);
;     }
;     __syncthreads();
;     if (t + 2 < NT) AT_LOAD((t + 2) * 64);
;   }
.Latt3_nodefer_9:
	s_waitcnt lgkmcnt(7)
	v_mfma_f32_16x16x32_bf16 v[132:135], v[212:215], v[196:199], v[132:135]
	v_mfma_f32_16x16x32_bf16 v[100:103], v[212:215], v[200:203], v[100:103]
	s_waitcnt lgkmcnt(6)
	v_mfma_f32_16x16x32_bf16 v[128:131], v[216:219], v[196:199], v[128:131]
	v_mfma_f32_16x16x32_bf16 v[96:99], v[216:219], v[200:203], v[96:99]
	s_waitcnt lgkmcnt(5)
	v_mfma_f32_16x16x32_bf16 v[124:127], v[220:223], v[196:199], v[124:127]
	v_mfma_f32_16x16x32_bf16 v[92:95], v[220:223], v[200:203], v[92:95]
	s_waitcnt lgkmcnt(4)
	v_mfma_f32_16x16x32_bf16 v[120:123], v[224:227], v[196:199], v[120:123]
	v_mfma_f32_16x16x32_bf16 v[88:91], v[224:227], v[200:203], v[88:91]
	s_waitcnt lgkmcnt(3)
	v_mfma_f32_16x16x32_bf16 v[116:119], v[180:183], v[196:199], v[116:119]
	v_mfma_f32_16x16x32_bf16 v[84:87], v[180:183], v[200:203], v[84:87]
	s_waitcnt lgkmcnt(2)
	v_mfma_f32_16x16x32_bf16 v[112:115], v[184:187], v[196:199], v[112:115]
	v_mfma_f32_16x16x32_bf16 v[80:83], v[184:187], v[200:203], v[80:83]
	s_waitcnt lgkmcnt(1)
	v_mfma_f32_16x16x32_bf16 v[108:111], v[188:191], v[196:199], v[108:111]
	v_mfma_f32_16x16x32_bf16 v[76:79], v[188:191], v[200:203], v[76:79]
	s_waitcnt lgkmcnt(0)
	v_mfma_f32_16x16x32_bf16 v[104:107], v[192:195], v[196:199], v[104:107]
	v_mfma_f32_16x16x32_bf16 v[72:75], v[192:195], v[200:203], v[72:75]
	s_branch .Latt4_tile_end
.Latt4_skip:
	s_bitcmp1_b32 s95, 0
	s_cbranch_scc0 .Latt4_skip_even
	v_add_u32_e32 v2, s70, v240
	v_add_u32_e32 v3, s70, v241
	v_add_u32_e32 v0, s70, v242
	s_waitcnt vmcnt(9)
	ds_write_b128 v2, v[64:67]
	s_waitcnt vmcnt(7)
	ds_write_b128 v2, v[68:71] offset:12288
	ds_write_b128 v3, v[60:63]
	s_waitcnt vmcnt(5)
	v_perm_b32 v2, v52, v56, s83
	ds_write_b32 v0, v2 offset:24576
	v_perm_b32 v2, v52, v56, s84
	v_xor_b32_e32 v3, 16, v0
	ds_write_b32 v3, v2 offset:24704
	v_perm_b32 v2, v53, v57, s83
	v_xor_b32_e32 v3, 32, v0
	ds_write_b32 v3, v2 offset:24832
	v_perm_b32 v2, v53, v57, s84
	v_xor_b32_e32 v3, 48, v0
	ds_write_b32 v3, v2 offset:24960
	v_perm_b32 v2, v54, v58, s83
	v_xor_b32_e32 v3, 64, v0
	ds_write_b32 v3, v2 offset:25088
	v_perm_b32 v2, v54, v58, s84
	v_xor_b32_e32 v3, s85, v0
	ds_write_b32 v3, v2 offset:25216
	v_perm_b32 v2, v55, v59, s83
	v_xor_b32_e32 v3, s86, v0
	ds_write_b32 v3, v2 offset:25344
	v_perm_b32 v2, v55, v59, s84
	v_xor_b32_e32 v3, s80, v0
	ds_write_b32 v3, v2 offset:25472
	s_add_u32 s2, s58, s66
	s_addc_u32 s3, s59, s67
	s_add_u32 s2, s2, 0x17680000
	s_addc_u32 s3, s3, 0
	s_add_u32 s96, s58, s68
	s_addc_u32 s97, s59, s69
	s_add_u32 s96, s96, 0x20000
	s_addc_u32 s97, s97, 0
	s_add_u32 s98, s2, 0x40000
	s_addc_u32 s99, s3, 0
	s_add_u32 s100, s2, 0x2000
	s_addc_u32 s101, s3, 0
	global_load_dwordx4 v[64:67], v243, s[2:3]
	global_load_dwordx4 v[60:63], v249, s[96:97]
	global_load_dwordx4 v[68:71], v243, s[98:99]
	global_load_dwordx4 v[52:55], v254, s[2:3] offset:256
	global_load_dwordx4 v[56:59], v254, s[100:101] offset:256
	s_branch .Latt4_tile_end
.Latt4_skip_even:
	v_add_u32_e32 v2, s70, v240
	v_add_u32_e32 v3, s70, v241
	v_add_u32_e32 v0, s70, v242
	s_waitcnt vmcnt(9)
	ds_write_b128 v2, v[228:231]
	s_waitcnt vmcnt(7)
	ds_write_b128 v2, v[232:235] offset:12288
	ds_write_b128 v3, v[236:239]
	s_waitcnt vmcnt(5)
	v_perm_b32 v2, v244, v250, s83
	ds_write_b32 v0, v2 offset:24576
	v_perm_b32 v2, v244, v250, s84
	v_xor_b32_e32 v3, 16, v0
	ds_write_b32 v3, v2 offset:24704
	v_perm_b32 v2, v245, v251, s83
	v_xor_b32_e32 v3, 32, v0
	ds_write_b32 v3, v2 offset:24832
	v_perm_b32 v2, v245, v251, s84
	v_xor_b32_e32 v3, 48, v0
	ds_write_b32 v3, v2 offset:24960
	v_perm_b32 v2, v246, v252, s83
	v_xor_b32_e32 v3, 64, v0
	ds_write_b32 v3, v2 offset:25088
	v_perm_b32 v2, v246, v252, s84
	v_xor_b32_e32 v3, s85, v0
	ds_write_b32 v3, v2 offset:25216
	v_perm_b32 v2, v247, v253, s83
	v_xor_b32_e32 v3, s86, v0
	ds_write_b32 v3, v2 offset:25344
	v_perm_b32 v2, v247, v253, s84
	v_xor_b32_e32 v3, s80, v0
	ds_write_b32 v3, v2 offset:25472
	s_cmp_eq_u32 s94, s95
	s_cbranch_scc1 .Latt4_tile_end
	s_add_u32 s2, s58, s66
	s_addc_u32 s3, s59, s67
	s_add_u32 s2, s2, 0x17680000
	s_addc_u32 s3, s3, 0
	s_add_u32 s96, s58, s68
	s_addc_u32 s97, s59, s69
	s_add_u32 s96, s96, 0x20000
	s_addc_u32 s97, s97, 0
	s_add_u32 s98, s2, 0x40000
	s_addc_u32 s99, s3, 0
	s_add_u32 s100, s2, 0x2000
	s_addc_u32 s101, s3, 0
	global_load_dwordx4 v[228:231], v243, s[2:3]
	global_load_dwordx4 v[236:239], v249, s[96:97]
	global_load_dwordx4 v[232:235], v243, s[98:99]
	global_load_dwordx4 v[244:247], v254, s[2:3] offset:256
	global_load_dwordx4 v[250:253], v254, s[100:101] offset:256
.Latt4_tile_end:
	s_waitcnt lgkmcnt(0)
	s_barrier
	s_add_i32 s77, s77, 64
	s_add_u32 s68, s68, 0x20000
	s_addc_u32 s69, s69, 0
	s_add_u32 s66, s66, 0x80000
	s_addc_u32 s67, s67, 0
	s_cmp_eq_u32 s94, s95
	s_cbranch_scc0 .LBB0_497
